# serpentine MFMA order in K-loop (accumulator chains + shared operand fragments), pointer SALU under MFMAs, hand-written relu2 epilogue fast path
# speedup vs baseline: 1.0104x; 1.0010x over previous
; #define PG8_STAGE(bufoff, gbase, voff) do { _Pragma("unroll") for (int _i = 0; _i < 2; ++_i) \
;     __builtin_amdgcn_global_load_lds((const unsigned*)((const char*)(gbase) + (voff)[_i]), (LAS unsigned*)(lds + (bufoff) + ldsw + _i * 8192), 16, 0, 0); } while (0)
; #define PG8_LDA(dst, b, h) do { _Pragma("unroll") for (int m = 0; m < 4; ++m) _Pragma("unroll") for (int k = 0; k < 2; ++k) dst[m][k] = *(const LAS bf16x8*)(lds + PG8_SA(b, h) + aoff + m * 2048 + k * 1024); } while (0)
; #define PG8_LDB(dst, b, h) do { _Pragma("unroll") for (int n = 0; n < 2; ++n) _Pragma("unroll") for (int k = 0; k < 2; ++k) dst[n][k] = *(const LAS bf16x8*)(lds + PG8_SB(b, h) + boff + n * 2048 + k * 1024); } while (0)
; #define PG8_MMA(ai, bj, At, Bt) do { __builtin_amdgcn_s_setprio(1); _Pragma("unroll") for (int m = 0; m < 4; ++m) _Pragma("unroll") for (int n = 0; n < 2; ++n) _Pragma("unroll") for (int k = 0; k < 2; ++k) \
;     acc[ai][bj][m][n] = __builtin_amdgcn_mfma_f32_16x16x32_bf16(Bt[n][k], At[m][k], acc[ai][bj][m][n], 0, 0, 0); __builtin_amdgcn_s_setprio(0); } while (0)
; #define PG8_WAIT_V(n) asm volatile("s_waitcnt vmcnt(" #n ")" ::: "memory")
; #define PG8_WAIT_L(n) asm volatile("s_waitcnt lgkmcnt(" #n ")" ::: "memory")
; #define PG8_BAR __builtin_amdgcn_s_barrier()
; __device__ __forceinline__ void gemm_phase(const Ctx& cx, LAS unsigned char* lds, const GemmDesc& g) {
;     ...
;     for (int t = 0; t < nt; t += 2) {
;       const bool last = (t == nt - 2);
;       const char* a1 = ktile_ptr(cA1, cA2, t + 1, ksplit, kstepA);
;       const char* a2 = last ? ktile_ptr(nA1, nA2, 0, ksplit, kstepA) : ktile_ptr(cA1, cA2, t + 2, ksplit, kstepA);
;       const char* a3 = last ? ktile_ptr(nA1, nA2, 1, ksplit, kstepA) : ktile_ptr(cA1, cA2, t + 3, ksplit, kstepA);
;       const char* b2 = last ? nB : cB + (size_t)(t + 2) * kstepB; const char* b3 = b2 + kstepB;
;       PG8_LDB(B0, 0, 0); PG8_LDB(B1, 0, 1); PG8_SCHED; PG8_LDA(At, 0, 0); PG8_STAGE(PG8_SA(1, 1), a1 + hstepA, voffA);
;       PG8_WAIT_V(8); PG8_WAIT_L(0); PG8_BAR; PG8_MMA(0, 0, At, B0); PG8_MMA(0, 1, At, B1); PG8_BAR; PG8_SCHED;
;       PG8_LDA(At, 0, 1); PG8_STAGE(PG8_SB(0, 0), b2, voffB); PG8_STAGE(PG8_SB(0, 1), b2 + hstepB, voffB); PG8_STAGE(PG8_SA(0, 0), a2, voffA);
;       PG8_WAIT_V(8); PG8_WAIT_L(0); PG8_BAR; PG8_MMA(1, 0, At, B0); PG8_MMA(1, 1, At, B1); PG8_BAR; PG8_SCHED;
.LBB0_358:
	s_add_i32 s7, s6, 1
	s_sub_i32 s14, s7, s41
	s_min_u32 s76, s7, s14
	s_cmp_lt_u32 s7, s41
	s_cselect_b32 s7, s9, s17
	s_cselect_b32 s54, s8, s16
	s_lshl_b64 s[14:15], s[76:77], s80
	s_add_u32 s55, s54, s14
	s_addc_u32 s73, s7, s15
	s_add_i32 s76, 0, 0x10000
	v_add_u32_e32 v96, s76, v252
	s_add_i32 vcc_lo, 0, 0x14000
	ds_read_b128 v[130:133], v96
	ds_read_b128 v[134:137], v96 offset:1024
	ds_read_b128 v[138:141], v96 offset:2048
	ds_read_b128 v[142:145], v96 offset:3072
	v_add_u32_e32 v96, vcc_lo, v252
	ds_read_b128 v[146:149], v96
	ds_read_b128 v[150:153], v96 offset:1024
	ds_read_b128 v[154:157], v96 offset:2048
	ds_read_b128 v[158:161], v96 offset:3072
	s_add_u32 s72, s55, s28
	s_addc_u32 s73, s73, s29
	v_lshl_add_u64 v[194:195], s[72:73], 0, v[210:211]
	s_add_i32 m0, s51, 0xc000
	ds_read_b128 v[162:165], v237
	ds_read_b128 v[166:169], v237 offset:1024
	ds_read_b128 v[170:173], v237 offset:2048
	ds_read_b128 v[174:177], v237 offset:3072
	ds_read_b128 v[178:181], v237 offset:4096
	ds_read_b128 v[182:185], v237 offset:5120
	ds_read_b128 v[186:189], v237 offset:6144
	ds_read_b128 v[190:193], v237 offset:7168
	global_load_lds_dwordx4 v[194:195], off
	v_lshl_add_u64 v[194:195], s[72:73], 0, v[212:213]
	s_add_i32 m0, s51, 0xe000
	s_nop 0
	global_load_lds_dwordx4 v[194:195], off
	s_waitcnt vmcnt(8)
	s_waitcnt lgkmcnt(0)
	s_barrier
	s_setprio 1
	s_waitcnt lgkmcnt(0)
	v_mfma_f32_16x16x32_bf16 v[126:129], v[130:133], v[162:165], v[126:129]
	v_mfma_f32_16x16x32_bf16 v[126:129], v[134:137], v[166:169], v[126:129]
	s_add_i32 s54, s6, 2
	s_cmp_lt_u32 s54, s41
	v_mfma_f32_16x16x32_bf16 v[122:125], v[142:145], v[166:169], v[122:125]
	s_cselect_b64 s[14:15], -1, 0
	s_and_b64 s[58:59], s[14:15], exec
	v_mfma_f32_16x16x32_bf16 v[122:125], v[138:141], v[162:165], v[122:125]
	s_cselect_b32 s7, 0, s41
	s_sub_i32 s7, s6, s7
	v_mfma_f32_16x16x32_bf16 v[118:121], v[146:149], v[162:165], v[118:121]
	s_add_i32 s76, s7, 2
	s_and_b64 s[14:15], s[14:15], exec
	v_mfma_f32_16x16x32_bf16 v[118:121], v[150:153], v[166:169], v[118:121]
	s_cselect_b32 s7, s9, s17
	s_cselect_b32 s58, s8, s16
	v_mfma_f32_16x16x32_bf16 v[114:117], v[158:161], v[166:169], v[114:117]
	s_lshl_b64 s[14:15], s[76:77], s80
	s_add_u32 s72, s58, s14
	v_mfma_f32_16x16x32_bf16 v[114:117], v[154:157], v[162:165], v[114:117]
	s_addc_u32 s7, s7, s15
	s_add_i32 s14, s6, 3
	v_mfma_f32_16x16x32_bf16 v[98:101], v[154:157], v[170:173], v[98:101]
	s_cmp_lt_u32 s14, s41
	s_cselect_b64 s[14:15], -1, 0
	v_mfma_f32_16x16x32_bf16 v[98:101], v[158:161], v[174:177], v[98:101]
	s_and_b64 s[58:59], s[14:15], exec
	s_cselect_b32 s58, 0, s41
	v_mfma_f32_16x16x32_bf16 v[102:105], v[150:153], v[174:177], v[102:105]
	s_sub_i32 s58, s6, s58
	s_add_i32 s76, s58, 3
	v_mfma_f32_16x16x32_bf16 v[102:105], v[146:149], v[170:173], v[102:105]
	s_and_b64 s[14:15], s[14:15], exec
	s_cselect_b32 s58, s9, s17
	v_mfma_f32_16x16x32_bf16 v[106:109], v[138:141], v[170:173], v[106:109]
	s_cselect_b32 s59, s8, s16
	s_lshl_b64 s[14:15], s[76:77], s80
	v_mfma_f32_16x16x32_bf16 v[106:109], v[142:145], v[174:177], v[106:109]
	s_add_u32 s59, s59, s14
	s_addc_u32 s58, s58, s15
	v_mfma_f32_16x16x32_bf16 v[110:113], v[134:137], v[174:177], v[110:113]
	s_cmp_eq_u32 s39, s6
	s_cselect_b32 s15, s13, s7
	v_mfma_f32_16x16x32_bf16 v[110:113], v[130:133], v[170:173], v[110:113]
	s_cselect_b32 s14, s12, s72
	s_cselect_b32 s7, s21, s58
	v_mfma_f32_16x16x32_bf16 v[92:95], v[130:133], v[178:181], v[92:95]
	s_cselect_b32 s6, s20, s59
	s_cselect_b32 s59, s97, s53
	v_mfma_f32_16x16x32_bf16 v[92:95], v[134:137], v[182:185], v[92:95]
	s_cselect_b32 s58, s96, s52
	s_mov_b32 s76, 0x10000
	v_mfma_f32_16x16x32_bf16 v[88:91], v[142:145], v[182:185], v[88:91]
	v_mfma_f32_16x16x32_bf16 v[88:91], v[138:141], v[178:181], v[88:91]
	v_mfma_f32_16x16x32_bf16 v[84:87], v[146:149], v[178:181], v[84:87]
	v_mfma_f32_16x16x32_bf16 v[84:87], v[150:153], v[182:185], v[84:87]
	v_mfma_f32_16x16x32_bf16 v[80:83], v[158:161], v[182:185], v[80:83]
	v_mfma_f32_16x16x32_bf16 v[80:83], v[154:157], v[178:181], v[80:83]
	v_mfma_f32_16x16x32_bf16 v[64:67], v[154:157], v[186:189], v[64:67]
	v_mfma_f32_16x16x32_bf16 v[64:67], v[158:161], v[190:193], v[64:67]
	v_mfma_f32_16x16x32_bf16 v[68:71], v[150:153], v[190:193], v[68:71]
	v_mfma_f32_16x16x32_bf16 v[68:71], v[146:149], v[186:189], v[68:71]
	v_mfma_f32_16x16x32_bf16 v[72:75], v[138:141], v[186:189], v[72:75]
	v_mfma_f32_16x16x32_bf16 v[72:75], v[142:145], v[190:193], v[72:75]
	v_mfma_f32_16x16x32_bf16 v[76:79], v[134:137], v[190:193], v[76:79]
	v_mfma_f32_16x16x32_bf16 v[76:79], v[130:133], v[186:189], v[76:79]
	s_setprio 0
	s_barrier
	s_add_i32 s55, s76, s36
	v_lshl_add_u64 v[194:195], s[58:59], 0, v[216:217]
	s_mov_b32 m0, s55
	ds_read_b128 v[162:165], v237 offset:16384
	ds_read_b128 v[166:169], v237 offset:17408
	ds_read_b128 v[170:173], v237 offset:18432
	ds_read_b128 v[174:177], v237 offset:19456
	ds_read_b128 v[178:181], v237 offset:20480
	ds_read_b128 v[182:185], v237 offset:21504
	ds_read_b128 v[186:189], v237 offset:22528
	ds_read_b128 v[190:193], v237 offset:23552
	global_load_lds_dwordx4 v[194:195], off
	s_add_i32 m0, s55, 0x2000
	v_lshl_add_u64 v[196:197], s[58:59], 0, v[214:215]
	s_add_u32 s58, s58, s30
	s_addc_u32 s59, s59, s31
	s_add_i32 s55, vcc_lo, s36
	global_load_lds_dwordx4 v[196:197], off
	v_lshl_add_u64 v[198:199], s[58:59], 0, v[216:217]
	s_mov_b32 m0, s55
	v_lshl_add_u64 v[200:201], s[58:59], 0, v[214:215]
	global_load_lds_dwordx4 v[198:199], off
	s_add_i32 m0, s55, 0x2000
	v_lshl_add_u64 v[202:203], s[14:15], 0, v[210:211]
	global_load_lds_dwordx4 v[200:201], off
	s_mov_b32 m0, s51
	s_nop 0
	global_load_lds_dwordx4 v[202:203], off
	v_lshl_add_u64 v[202:203], s[14:15], 0, v[212:213]
	s_mov_b32 m0, s43
	s_nop 0
	global_load_lds_dwordx4 v[202:203], off
	s_waitcnt vmcnt(8)
	s_waitcnt lgkmcnt(0)
	s_barrier
; #define PG8_STAGE(bufoff, gbase, voff) do { _Pragma("unroll") for (int _i = 0; _i < 2; ++_i) \
;     __builtin_amdgcn_global_load_lds((const unsigned*)((const char*)(gbase) + (voff)[_i]), (LAS unsigned*)(lds + (bufoff) + ldsw + _i * 8192), 16, 0, 0); } while (0)
; #define PG8_LDA(dst, b, h) do { _Pragma("unroll") for (int m = 0; m < 4; ++m) _Pragma("unroll") for (int k = 0; k < 2; ++k) dst[m][k] = *(const LAS bf16x8*)(lds + PG8_SA(b, h) + aoff + m * 2048 + k * 1024); } while (0)
; #define PG8_LDB(dst, b, h) do { _Pragma("unroll") for (int n = 0; n < 2; ++n) _Pragma("unroll") for (int k = 0; k < 2; ++k) dst[n][k] = *(const LAS bf16x8*)(lds + PG8_SB(b, h) + boff + n * 2048 + k * 1024); } while (0)
; #define PG8_MMA(ai, bj, At, Bt) do { __builtin_amdgcn_s_setprio(1); _Pragma("unroll") for (int m = 0; m < 4; ++m) _Pragma("unroll") for (int n = 0; n < 2; ++n) _Pragma("unroll") for (int k = 0; k < 2; ++k) \
;     acc[ai][bj][m][n] = __builtin_amdgcn_mfma_f32_16x16x32_bf16(Bt[n][k], At[m][k], acc[ai][bj][m][n], 0, 0, 0); __builtin_amdgcn_s_setprio(0); } while (0)
; #define PG8_WAIT_V(n) asm volatile("s_waitcnt vmcnt(" #n ")" ::: "memory")
; #define PG8_WAIT_L(n) asm volatile("s_waitcnt lgkmcnt(" #n ")" ::: "memory")
; #define PG8_BAR __builtin_amdgcn_s_barrier()
; #define PG8_SCHED __builtin_amdgcn_sched_barrier(0)
; __device__ __forceinline__ void gemm_phase(const Ctx& cx, LAS unsigned char* lds, const GemmDesc& g) {
;     ...
;       PG8_WAIT_V(8); PG8_WAIT_L(0); PG8_BAR; PG8_MMA(1, 0, At, B0); PG8_MMA(1, 1, At, B1); PG8_BAR; PG8_SCHED;
;       PG8_LDB(B0, 1, 0); PG8_LDB(B1, 1, 1); PG8_SCHED; PG8_LDA(At, 1, 0); PG8_STAGE(PG8_SA(0, 1), a2 + hstepA, voffA);
;       PG8_WAIT_V(8); PG8_WAIT_L(0); PG8_BAR; PG8_MMA(0, 0, At, B0); PG8_MMA(0, 1, At, B1); PG8_BAR; PG8_SCHED;
	s_setprio 1
	s_waitcnt lgkmcnt(0)
	v_mfma_f32_16x16x32_bf16 v[60:63], v[130:133], v[162:165], v[60:63]
	v_mfma_f32_16x16x32_bf16 v[60:63], v[134:137], v[166:169], v[60:63]
	v_mfma_f32_16x16x32_bf16 v[56:59], v[142:145], v[166:169], v[56:59]
	v_mfma_f32_16x16x32_bf16 v[56:59], v[138:141], v[162:165], v[56:59]
	v_mfma_f32_16x16x32_bf16 v[52:55], v[146:149], v[162:165], v[52:55]
	v_mfma_f32_16x16x32_bf16 v[52:55], v[150:153], v[166:169], v[52:55]
	v_mfma_f32_16x16x32_bf16 v[48:51], v[158:161], v[166:169], v[48:51]
	v_mfma_f32_16x16x32_bf16 v[48:51], v[154:157], v[162:165], v[48:51]
	v_mfma_f32_16x16x32_bf16 v[32:35], v[154:157], v[170:173], v[32:35]
	v_mfma_f32_16x16x32_bf16 v[32:35], v[158:161], v[174:177], v[32:35]
	v_mfma_f32_16x16x32_bf16 v[36:39], v[150:153], v[174:177], v[36:39]
	v_mfma_f32_16x16x32_bf16 v[36:39], v[146:149], v[170:173], v[36:39]
	v_mfma_f32_16x16x32_bf16 v[40:43], v[138:141], v[170:173], v[40:43]
	v_mfma_f32_16x16x32_bf16 v[40:43], v[142:145], v[174:177], v[40:43]
	v_mfma_f32_16x16x32_bf16 v[44:47], v[134:137], v[174:177], v[44:47]
	v_mfma_f32_16x16x32_bf16 v[44:47], v[130:133], v[170:173], v[44:47]
	v_mfma_f32_16x16x32_bf16 v[28:31], v[130:133], v[178:181], v[28:31]
	v_mfma_f32_16x16x32_bf16 v[28:31], v[134:137], v[182:185], v[28:31]
	v_mfma_f32_16x16x32_bf16 v[24:27], v[142:145], v[182:185], v[24:27]
	v_mfma_f32_16x16x32_bf16 v[24:27], v[138:141], v[178:181], v[24:27]
	v_mfma_f32_16x16x32_bf16 v[20:23], v[146:149], v[178:181], v[20:23]
	v_mfma_f32_16x16x32_bf16 v[20:23], v[150:153], v[182:185], v[20:23]
	v_mfma_f32_16x16x32_bf16 v[16:19], v[158:161], v[182:185], v[16:19]
	v_mfma_f32_16x16x32_bf16 v[16:19], v[154:157], v[178:181], v[16:19]
	v_mfma_f32_16x16x32_bf16 v[0:3], v[154:157], v[186:189], v[0:3]
	v_mfma_f32_16x16x32_bf16 v[0:3], v[158:161], v[190:193], v[0:3]
	v_mfma_f32_16x16x32_bf16 v[4:7], v[150:153], v[190:193], v[4:7]
	v_mfma_f32_16x16x32_bf16 v[4:7], v[146:149], v[186:189], v[4:7]
	v_mfma_f32_16x16x32_bf16 v[8:11], v[138:141], v[186:189], v[8:11]
	v_mfma_f32_16x16x32_bf16 v[8:11], v[142:145], v[190:193], v[8:11]
	v_mfma_f32_16x16x32_bf16 v[12:15], v[134:137], v[190:193], v[12:15]
	v_mfma_f32_16x16x32_bf16 v[12:15], v[130:133], v[186:189], v[12:15]
	s_setprio 0
	s_barrier
	s_add_i32 s55, 0, 0x18000
	v_add_u32_e32 v96, s55, v252
	s_add_i32 s58, 0, 0x1c000
	ds_read_b128 v[130:133], v96
	ds_read_b128 v[134:137], v96 offset:1024
	ds_read_b128 v[138:141], v96 offset:2048
	ds_read_b128 v[142:145], v96 offset:3072
	v_add_u32_e32 v96, s58, v252
	ds_read_b128 v[146:149], v96
	ds_read_b128 v[150:153], v96 offset:1024
	ds_read_b128 v[154:157], v96 offset:2048
	ds_read_b128 v[158:161], v96 offset:3072
	s_add_u32 s14, s14, s28
	s_addc_u32 s15, s15, s29
	s_mov_b32 m0, s40
	v_lshl_add_u64 v[202:203], s[14:15], 0, v[210:211]
	ds_read_b128 v[162:165], v237 offset:32768
	ds_read_b128 v[166:169], v237 offset:33792
	ds_read_b128 v[170:173], v237 offset:34816
	ds_read_b128 v[174:177], v237 offset:35840
	ds_read_b128 v[178:181], v237 offset:36864
	ds_read_b128 v[182:185], v237 offset:37888
	ds_read_b128 v[186:189], v237 offset:38912
	ds_read_b128 v[190:193], v237 offset:39936
	global_load_lds_dwordx4 v[202:203], off
	v_lshl_add_u64 v[202:203], s[14:15], 0, v[212:213]
	s_mov_b32 m0, s37
	s_nop 0
	global_load_lds_dwordx4 v[202:203], off
	s_waitcnt vmcnt(8)
	s_waitcnt lgkmcnt(0)
	s_barrier
	s_setprio 1
	s_waitcnt lgkmcnt(0)
	v_mfma_f32_16x16x32_bf16 v[126:129], v[130:133], v[162:165], v[126:129]
	v_mfma_f32_16x16x32_bf16 v[126:129], v[134:137], v[166:169], v[126:129]
	v_mfma_f32_16x16x32_bf16 v[122:125], v[142:145], v[166:169], v[122:125]
	v_mfma_f32_16x16x32_bf16 v[122:125], v[138:141], v[162:165], v[122:125]
	v_mfma_f32_16x16x32_bf16 v[118:121], v[146:149], v[162:165], v[118:121]
	v_mfma_f32_16x16x32_bf16 v[118:121], v[150:153], v[166:169], v[118:121]
	v_mfma_f32_16x16x32_bf16 v[114:117], v[158:161], v[166:169], v[114:117]
	v_mfma_f32_16x16x32_bf16 v[114:117], v[154:157], v[162:165], v[114:117]
	v_mfma_f32_16x16x32_bf16 v[98:101], v[154:157], v[170:173], v[98:101]
	v_mfma_f32_16x16x32_bf16 v[98:101], v[158:161], v[174:177], v[98:101]
	v_mfma_f32_16x16x32_bf16 v[102:105], v[150:153], v[174:177], v[102:105]
	v_mfma_f32_16x16x32_bf16 v[102:105], v[146:149], v[170:173], v[102:105]
	v_mfma_f32_16x16x32_bf16 v[106:109], v[138:141], v[170:173], v[106:109]
	v_mfma_f32_16x16x32_bf16 v[106:109], v[142:145], v[174:177], v[106:109]
	v_mfma_f32_16x16x32_bf16 v[110:113], v[134:137], v[174:177], v[110:113]
	v_mfma_f32_16x16x32_bf16 v[110:113], v[130:133], v[170:173], v[110:113]
	v_mfma_f32_16x16x32_bf16 v[92:95], v[130:133], v[178:181], v[92:95]
	v_mfma_f32_16x16x32_bf16 v[92:95], v[134:137], v[182:185], v[92:95]
	v_mfma_f32_16x16x32_bf16 v[88:91], v[142:145], v[182:185], v[88:91]
	v_mfma_f32_16x16x32_bf16 v[88:91], v[138:141], v[178:181], v[88:91]
	v_mfma_f32_16x16x32_bf16 v[84:87], v[146:149], v[178:181], v[84:87]
	v_mfma_f32_16x16x32_bf16 v[84:87], v[150:153], v[182:185], v[84:87]
	v_mfma_f32_16x16x32_bf16 v[80:83], v[158:161], v[182:185], v[80:83]
	v_mfma_f32_16x16x32_bf16 v[80:83], v[154:157], v[178:181], v[80:83]
	v_mfma_f32_16x16x32_bf16 v[64:67], v[154:157], v[186:189], v[64:67]
	v_mfma_f32_16x16x32_bf16 v[64:67], v[158:161], v[190:193], v[64:67]
	v_mfma_f32_16x16x32_bf16 v[68:71], v[150:153], v[190:193], v[68:71]
	v_mfma_f32_16x16x32_bf16 v[68:71], v[146:149], v[186:189], v[68:71]
	v_mfma_f32_16x16x32_bf16 v[72:75], v[138:141], v[186:189], v[72:75]
	v_mfma_f32_16x16x32_bf16 v[72:75], v[142:145], v[190:193], v[72:75]
	v_mfma_f32_16x16x32_bf16 v[76:79], v[134:137], v[190:193], v[76:79]
	v_mfma_f32_16x16x32_bf16 v[76:79], v[130:133], v[186:189], v[76:79]
	s_setprio 0
	s_barrier
; #define PG8_STAGE(bufoff, gbase, voff) do { _Pragma("unroll") for (int _i = 0; _i < 2; ++_i) \
;     __builtin_amdgcn_global_load_lds((const unsigned*)((const char*)(gbase) + (voff)[_i]), (LAS unsigned*)(lds + (bufoff) + ldsw + _i * 8192), 16, 0, 0); } while (0)
; #define PG8_LDA(dst, b, h) do { _Pragma("unroll") for (int m = 0; m < 4; ++m) _Pragma("unroll") for (int k = 0; k < 2; ++k) dst[m][k] = *(const LAS bf16x8*)(lds + PG8_SA(b, h) + aoff + m * 2048 + k * 1024); } while (0)
; #define PG8_MMA(ai, bj, At, Bt) do { __builtin_amdgcn_s_setprio(1); _Pragma("unroll") for (int m = 0; m < 4; ++m) _Pragma("unroll") for (int n = 0; n < 2; ++n) _Pragma("unroll") for (int k = 0; k < 2; ++k) \
;     acc[ai][bj][m][n] = __builtin_amdgcn_mfma_f32_16x16x32_bf16(Bt[n][k], At[m][k], acc[ai][bj][m][n], 0, 0, 0); __builtin_amdgcn_s_setprio(0); } while (0)
; #define PG8_WAIT_V(n) asm volatile("s_waitcnt vmcnt(" #n ")" ::: "memory")
; #define PG8_WAIT_L(n) asm volatile("s_waitcnt lgkmcnt(" #n ")" ::: "memory")
; #define PG8_BAR __builtin_amdgcn_s_barrier()
; #define PG8_SCHED __builtin_amdgcn_sched_barrier(0)
; __device__ __forceinline__ void gemm_phase(const Ctx& cx, LAS unsigned char* lds, const GemmDesc& g) {
;     ...
;       PG8_LDA(At, 1, 1); PG8_STAGE(PG8_SB(1, 0), b3, voffB); PG8_STAGE(PG8_SB(1, 1), b3 + hstepB, voffB); PG8_STAGE(PG8_SA(1, 0), a3, voffA);
;       PG8_WAIT_V(8); PG8_WAIT_L(0); PG8_BAR; PG8_MMA(1, 0, At, B0); PG8_MMA(1, 1, At, B1); PG8_BAR; PG8_SCHED;
;     }
;     if (wr == 0) PG8_BAR;
	s_add_i32 s14, s55, s36
	v_lshl_add_u64 v[194:195], v[194:195], 0, s[92:93]
	s_mov_b32 m0, s14
	ds_read_b128 v[162:165], v237 offset:49152
	ds_read_b128 v[166:169], v237 offset:50176
	ds_read_b128 v[170:173], v237 offset:51200
	ds_read_b128 v[174:177], v237 offset:52224
	ds_read_b128 v[178:181], v237 offset:53248
	ds_read_b128 v[182:185], v237 offset:54272
	ds_read_b128 v[186:189], v237 offset:55296
	ds_read_b128 v[190:193], v237 offset:56320
	global_load_lds_dwordx4 v[194:195], off
	v_lshl_add_u64 v[194:195], v[196:197], 0, s[92:93]
	s_add_i32 m0, s14, 0x2000
	s_add_i32 s14, s58, s36
	global_load_lds_dwordx4 v[194:195], off
	v_lshl_add_u64 v[194:195], v[198:199], 0, s[92:93]
	s_mov_b32 m0, s14
	s_nop 0
	global_load_lds_dwordx4 v[194:195], off
	v_lshl_add_u64 v[194:195], v[200:201], 0, s[92:93]
	s_add_i32 m0, s14, 0x2000
	s_nop 0
	global_load_lds_dwordx4 v[194:195], off
	v_lshl_add_u64 v[194:195], s[6:7], 0, v[210:211]
	s_mov_b32 m0, s0
	s_nop 0
	global_load_lds_dwordx4 v[194:195], off
	v_lshl_add_u64 v[194:195], s[6:7], 0, v[212:213]
	s_mov_b32 m0, s1
	s_nop 0
	global_load_lds_dwordx4 v[194:195], off
	s_waitcnt vmcnt(8)
	s_waitcnt lgkmcnt(0)
	s_barrier
	s_setprio 1
	s_waitcnt lgkmcnt(0)
	v_mfma_f32_16x16x32_bf16 v[60:63], v[130:133], v[162:165], v[60:63]
	v_mfma_f32_16x16x32_bf16 v[60:63], v[134:137], v[166:169], v[60:63]
	v_mfma_f32_16x16x32_bf16 v[56:59], v[142:145], v[166:169], v[56:59]
	v_mfma_f32_16x16x32_bf16 v[56:59], v[138:141], v[162:165], v[56:59]
	v_mfma_f32_16x16x32_bf16 v[52:55], v[146:149], v[162:165], v[52:55]
	v_mfma_f32_16x16x32_bf16 v[52:55], v[150:153], v[166:169], v[52:55]
	v_mfma_f32_16x16x32_bf16 v[48:51], v[158:161], v[166:169], v[48:51]
	v_mfma_f32_16x16x32_bf16 v[48:51], v[154:157], v[162:165], v[48:51]
	v_mfma_f32_16x16x32_bf16 v[32:35], v[154:157], v[170:173], v[32:35]
	v_mfma_f32_16x16x32_bf16 v[32:35], v[158:161], v[174:177], v[32:35]
	v_mfma_f32_16x16x32_bf16 v[36:39], v[150:153], v[174:177], v[36:39]
	v_mfma_f32_16x16x32_bf16 v[36:39], v[146:149], v[170:173], v[36:39]
	v_mfma_f32_16x16x32_bf16 v[40:43], v[138:141], v[170:173], v[40:43]
	v_mfma_f32_16x16x32_bf16 v[40:43], v[142:145], v[174:177], v[40:43]
	v_mfma_f32_16x16x32_bf16 v[44:47], v[134:137], v[174:177], v[44:47]
	v_mfma_f32_16x16x32_bf16 v[44:47], v[130:133], v[170:173], v[44:47]
	v_mfma_f32_16x16x32_bf16 v[28:31], v[130:133], v[178:181], v[28:31]
	v_mfma_f32_16x16x32_bf16 v[28:31], v[134:137], v[182:185], v[28:31]
	v_mfma_f32_16x16x32_bf16 v[24:27], v[142:145], v[182:185], v[24:27]
	v_mfma_f32_16x16x32_bf16 v[24:27], v[138:141], v[178:181], v[24:27]
	v_mfma_f32_16x16x32_bf16 v[20:23], v[146:149], v[178:181], v[20:23]
	v_mfma_f32_16x16x32_bf16 v[20:23], v[150:153], v[182:185], v[20:23]
	v_mfma_f32_16x16x32_bf16 v[16:19], v[158:161], v[182:185], v[16:19]
	v_mfma_f32_16x16x32_bf16 v[16:19], v[154:157], v[178:181], v[16:19]
	v_mfma_f32_16x16x32_bf16 v[0:3], v[154:157], v[186:189], v[0:3]
	v_mfma_f32_16x16x32_bf16 v[0:3], v[158:161], v[190:193], v[0:3]
	v_mfma_f32_16x16x32_bf16 v[4:7], v[150:153], v[190:193], v[4:7]
	v_mfma_f32_16x16x32_bf16 v[4:7], v[146:149], v[186:189], v[4:7]
	v_mfma_f32_16x16x32_bf16 v[8:11], v[138:141], v[186:189], v[8:11]
	v_mfma_f32_16x16x32_bf16 v[8:11], v[142:145], v[190:193], v[8:11]
	v_mfma_f32_16x16x32_bf16 v[12:15], v[134:137], v[190:193], v[12:15]
	v_mfma_f32_16x16x32_bf16 v[12:15], v[130:133], v[186:189], v[12:15]
	s_setprio 0
	s_barrier
	s_add_u32 s52, s52, 0x100
	s_addc_u32 s53, s53, 0
	s_cmp_ge_u32 s54, s10
	s_mov_b32 s6, s54
	s_cbranch_scc0 .LBB0_358
	v_readlane_b32 s6, v255, 19
	v_readlane_b32 s7, v255, 20
	s_and_b64 vcc, exec, s[6:7]
	s_cbranch_vccz .LBB0_361
	s_barrier
